# v20 + scan phase: GLA pre-pass items shared by GLA, RG-LRU and team workgroups (instead of GLA, HGRN2, team): HGRN2 long jobs are the critical ones, RG-LRU ones have slack
# baseline (speedup 1.0000x reference)
.LBB0_80:
	v_readlane_b32 s22, v248, 1
	v_readlane_b32 s23, v248, 2
	s_add_u32 s0, s22, 0x72d00000
	s_addc_u32 s1, s23, 0
	v_writelane_b32 v249, s0, 4
	v_readlane_b32 s24, v248, 7
	v_readlane_b32 s48, v248, 26
	v_writelane_b32 v249, s1, 5
	s_ashr_i32 s0, s24, 31
	v_readlane_b32 s50, v248, 28
	v_writelane_b32 v249, s0, 6
	v_readlane_b32 s51, v248, 29
	s_add_u32 s0, s50, 0x2000
	s_addc_u32 s1, s51, 0
	v_writelane_b32 v249, s0, 7
	s_cmpk_lg_i32 s24, 0x100
	v_readlane_b32 s13, v248, 43
	v_writelane_b32 v249, s1, 8
	s_cselect_b64 s[0:1], -1, 0
	v_writelane_b32 v249, s0, 9
	s_cmpk_lt_i32 s13, 0x1400
	v_readlane_b32 s21, v248, 0
	v_writelane_b32 v249, s1, 10
	s_cselect_b64 s[0:1], -1, 0
	v_writelane_b32 v249, s0, 11
	v_readlane_b32 s49, v248, 27
	v_mov_b32_e32 v34, 0
	v_writelane_b32 v249, s1, 12
	s_add_i32 s0, s13, 0x3c80
	s_add_u32 s9, s22, 0x24500000
	s_addc_u32 s12, s23, 0
	s_add_u32 s5, s22, 0x1e500000
	v_writelane_b32 v249, s0, 13
	s_addc_u32 s11, s23, 0
	s_add_i32 s0, s21, 0xffffff97
	s_cmpk_lt_u32 s0, 0x67
	s_cselect_b64 s[0:1], -1, 0
	v_writelane_b32 v249, s0, 14
	v_mov_b32_e32 v219, 1
	v_mov_b32_e32 v222, 0x358637bd
	v_writelane_b32 v249, s1, 15
	s_add_i32 s0, s13, 0xfffffcb8
	s_cmpk_lt_i32 s0, 0x1400
	s_cselect_b64 s[0:1], -1, 0
	v_writelane_b32 v249, s0, 16
	v_mov_b32_e32 v223, 0x260
	v_mov_b32_e32 v224, 0x3ecc95a3
	v_writelane_b32 v249, s1, 17
	s_add_i32 s0, s13, 0x3938
	v_writelane_b32 v249, s0, 18
	s_add_u32 s0, s22, 0x4200
	s_addc_u32 s1, s23, 0
	v_writelane_b32 v249, s0, 19
	v_mov_b32_e32 v225, 0x3e2aaaab
	v_mov_b64_e32 v[164:165], 0x969
	v_writelane_b32 v249, s1, 20
	s_add_u32 s0, s22, 0x4400
	s_addc_u32 s1, s23, 0
	v_writelane_b32 v249, s0, 21
	v_mov_b64_e32 v[166:167], 0x968
	v_mov_b32_e32 v226, 0x41b17218
	v_writelane_b32 v249, s1, 22
	s_add_u32 s0, s22, 0x4500
	s_addc_u32 s1, s23, 0
	v_writelane_b32 v249, s0, 23
	v_mov_b64_e32 v[168:169], 0x630
	v_mov_b64_e32 v[170:171], 0x62f
	v_writelane_b32 v249, s1, 24
	s_add_u32 s0, s22, 0x4600
	s_addc_u32 s1, s23, 0
	v_writelane_b32 v249, s0, 25
	v_mov_b32_e32 v227, 0x1e040
	v_mov_b32_e32 v228, 2
	v_writelane_b32 v249, s1, 26
	s_add_u32 s0, s22, 0x4700
	s_addc_u32 s1, s23, 0
	v_writelane_b32 v249, s0, 27
	v_mov_b32_e32 v230, 0x3000
	v_mov_b32_e32 v231, 0x7f800000
	v_writelane_b32 v249, s1, 28
	s_add_u32 s0, s22, 0x4800
	s_addc_u32 s1, s23, 0
	v_writelane_b32 v249, s0, 29
	v_readlane_b32 s52, v248, 30
	v_readlane_b32 s53, v248, 31
	v_writelane_b32 v249, s1, 30
	s_add_u32 s0, s22, 0x4900
	s_addc_u32 s1, s23, 0
	v_writelane_b32 v249, s0, 31
	v_readlane_b32 s54, v248, 32
	v_readlane_b32 s55, v248, 33
	v_writelane_b32 v249, s1, 32
	s_add_u32 s0, s22, 0x4a00
	s_addc_u32 s1, s23, 0
	v_writelane_b32 v249, s0, 33
	v_readlane_b32 s56, v248, 34
	v_readlane_b32 s57, v248, 35
	v_writelane_b32 v249, s1, 34
	s_add_u32 s0, s22, 0x4b00
	s_addc_u32 s1, s23, 0
	v_writelane_b32 v249, s0, 35
	v_readlane_b32 s58, v248, 36
	v_readlane_b32 s59, v248, 37
	v_writelane_b32 v249, s1, 36
	s_add_u32 s0, s22, 0x4c00
	s_addc_u32 s1, s23, 0
	v_writelane_b32 v249, s0, 37
	v_readlane_b32 s60, v248, 38
	v_readlane_b32 s61, v248, 39
	v_writelane_b32 v249, s1, 38
	s_add_u32 s0, s22, 0x4d00
	s_addc_u32 s1, s23, 0
	v_writelane_b32 v249, s0, 39
	v_readlane_b32 s62, v248, 40
	v_readlane_b32 s63, v248, 41
	v_writelane_b32 v249, s1, 40
	s_add_u32 s0, s22, 0x4e00
	s_addc_u32 s1, s23, 0
	v_writelane_b32 v249, s0, 41
	s_nop 1
	v_writelane_b32 v249, s1, 42
	s_add_u32 s0, s22, 0x4f00
	s_addc_u32 s1, s23, 0
	v_writelane_b32 v249, s0, 43
	s_nop 1
	v_writelane_b32 v249, s1, 44
	s_add_u32 s0, s22, 0x5000
	s_addc_u32 s1, s23, 0
	v_writelane_b32 v249, s0, 45
	s_nop 1
	v_writelane_b32 v249, s1, 46
	s_add_u32 s0, s22, 0x5100
	s_addc_u32 s1, s23, 0
	v_writelane_b32 v249, s0, 47
	s_nop 1
	v_writelane_b32 v249, s1, 48
	s_add_u32 s0, s22, 0x5200
	s_addc_u32 s1, s23, 0
	v_writelane_b32 v249, s0, 49
	s_nop 1
	v_writelane_b32 v249, s1, 50
	s_add_u32 s0, s22, 0x5300
	s_addc_u32 s1, s23, 0
	v_writelane_b32 v249, s0, 51
	s_cmp_eq_u32 s46, 15
	s_nop 0
	v_writelane_b32 v249, s1, 52
	s_cselect_b64 s[0:1], -1, 0
	v_writelane_b32 v249, s0, 53
	s_cmp_eq_u32 s46, 14
	s_nop 0
	v_writelane_b32 v249, s1, 54
	s_cselect_b64 s[0:1], -1, 0
	v_writelane_b32 v249, s0, 55
	s_cmp_eq_u32 s46, 13
	s_nop 0
	v_writelane_b32 v249, s1, 56
	s_cselect_b64 s[0:1], -1, 0
	v_writelane_b32 v249, s0, 57
	s_cmp_eq_u32 s46, 12
	s_nop 0
	v_writelane_b32 v249, s1, 58
	s_cselect_b64 s[0:1], -1, 0
	v_writelane_b32 v249, s0, 59
	s_cmp_eq_u32 s46, 11
	s_nop 0
	v_writelane_b32 v249, s1, 60
	s_cselect_b64 s[0:1], -1, 0
	v_writelane_b32 v249, s0, 61
	s_cmp_eq_u32 s46, 10
	s_nop 0
	v_writelane_b32 v249, s1, 62
	s_cselect_b64 s[0:1], -1, 0
	v_writelane_b32 v249, s0, 63
	s_cmp_eq_u32 s46, 9
	s_nop 0
	v_writelane_b32 v250, s1, 0
	s_cselect_b64 s[0:1], -1, 0
	v_writelane_b32 v250, s0, 1
	s_cmp_eq_u32 s46, 8
	s_nop 0
	v_writelane_b32 v250, s1, 2
	s_cselect_b64 s[0:1], -1, 0
	v_writelane_b32 v250, s0, 3
	s_cmp_eq_u32 s46, 7
	s_nop 0
	v_writelane_b32 v250, s1, 4
	s_cselect_b64 s[0:1], -1, 0
	v_writelane_b32 v250, s0, 5
	s_cmp_eq_u32 s46, 6
	s_nop 0
	v_writelane_b32 v250, s1, 6
	s_cselect_b64 s[0:1], -1, 0
	v_writelane_b32 v250, s0, 7
	s_cmp_eq_u32 s46, 5
	s_nop 0
	v_writelane_b32 v250, s1, 8
	s_cselect_b64 s[0:1], -1, 0
	v_writelane_b32 v250, s0, 9
	s_cmp_eq_u32 s46, 4
	s_nop 0
	v_writelane_b32 v250, s1, 10
	s_cselect_b64 s[0:1], -1, 0
	v_writelane_b32 v250, s0, 11
	s_cmp_eq_u32 s46, 3
	s_nop 0
	v_writelane_b32 v250, s1, 12
	s_cselect_b64 s[0:1], -1, 0
	v_writelane_b32 v250, s0, 13
	s_cmp_eq_u32 s46, 2
	s_nop 0
	v_writelane_b32 v250, s1, 14
	s_cselect_b64 s[0:1], -1, 0
	v_writelane_b32 v250, s0, 15
	s_cmp_eq_u32 s46, 1
	s_nop 0
	v_writelane_b32 v250, s1, 16
	s_cselect_b64 s[0:1], -1, 0
	v_writelane_b32 v250, s0, 17
	s_cmp_eq_u32 s46, 0
	s_nop 0
	v_writelane_b32 v250, s1, 18
	s_cselect_b64 s[0:1], -1, 0
	v_writelane_b32 v250, s0, 19
	s_nop 1
	v_writelane_b32 v250, s1, 20
	s_lshl_b32 s0, s46, 8
	s_add_u32 s0, s2, s0
	s_addc_u32 s1, s3, 0
	s_add_u32 s2, s0, 0x1400
	s_addc_u32 s3, s1, 0
	v_writelane_b32 v250, s2, 21
	s_add_u32 s0, s0, 0x2400
	s_addc_u32 s1, s1, 0
	v_writelane_b32 v250, s3, 22
	v_writelane_b32 v250, s0, 23
	s_nop 1
	v_writelane_b32 v250, s1, 24
	s_add_u32 s0, s22, 0x7400
	s_addc_u32 s1, s23, 0
	v_writelane_b32 v250, s0, 25
	s_nop 1
	v_writelane_b32 v250, s1, 26
	s_add_u32 s0, s22, 0x7500
	s_addc_u32 s1, s23, 0
	v_writelane_b32 v250, s0, 27
	s_cmpk_lt_i32 s21, 0x220
	s_nop 0
	v_writelane_b32 v250, s1, 28
	s_cselect_b64 s[0:1], -1, 0
	v_writelane_b32 v250, s0, 29
	s_ashr_i32 s14, s21, 31
	s_add_i32 s8, s21, 0xffffff40
	v_writelane_b32 v250, s1, 30
	s_lshr_b32 s0, s14, 26
	s_add_i32 s0, s21, s0
	s_ashr_i32 s7, s0, 6
	s_add_i32 s0, s24, 0xffffff40
	v_writelane_b32 v250, s0, 31
	s_sub_i32 s0, s21, 64
	s_cmpk_lt_i32 s21, 0x80
	s_cselect_b32 s25, s21, s0
	s_cmpk_lt_i32 s25, 0x220
	v_writelane_b32 v250, s0, 32
	s_cselect_b64 s[0:1], -1, 0
	v_writelane_b32 v250, s0, 33
	s_nop 1
	v_writelane_b32 v250, s1, 34
	s_add_u32 s0, s22, 0x12000
	v_writelane_b32 v250, s0, 35
	s_addc_u32 s0, s23, 0
	v_writelane_b32 v250, s0, 36
	s_add_i32 s0, s21, 0xffffff80
	v_writelane_b32 v250, s0, 37
	s_add_i32 s0, s21, 1
	v_writelane_b32 v250, s0, 38
	s_sub_i32 s0, s21, 63
	v_writelane_b32 v250, s0, 39
	s_add_i32 s0, s21, 0xffffff81
	s_cmpk_gt_i32 s21, 0xbf
	v_writelane_b32 v250, s0, 40
	s_cselect_b64 s[0:1], -1, 0
	s_cmpk_eq_i32 s24, 0x100
	s_cselect_b64 s[26:27], -1, 0
	s_and_b64 s[2:3], s[26:27], exec
	s_movk_i32 s2, 0x200
	s_cselect_b32 s6, s2, 0x210
	s_movk_i32 s2, 0x2000
	s_cselect_b32 s2, s2, 0x2100
	v_writelane_b32 v250, s2, 41
	s_cselect_b32 s19, 32, 33
	s_cselect_b32 s10, 0xc80, 0
	s_and_b64 s[0:1], s[0:1], s[26:27]
	v_writelane_b32 v250, s0, 42
	s_nop 1
	v_writelane_b32 v250, s1, 43
	s_add_u32 s0, s22, 0x10000
	v_writelane_b32 v250, s0, 44
	s_addc_u32 s0, s23, 0
	v_writelane_b32 v250, s0, 45
	s_lshl_b32 s0, s8, 3
	s_add_i32 s15, s33, s0
	s_cmpk_lt_i32 s21, 0xf0
	s_mul_hi_i32 s0, s8, 0x55555556
	s_cselect_b64 s[2:3], -1, 0
	s_lshr_b32 s1, s0, 31
	s_add_i32 s1, s0, s1
	s_mul_i32 s0, s1, -3
	v_writelane_b32 v250, s2, 46
	s_add_i32 s0, s0, s8
	s_mul_i32 s4, s1, 0x300000
	v_writelane_b32 v250, s3, 47
	s_lshl_b32 s2, s0, 11
	s_ashr_i32 s3, s2, 31
	s_lshl_b64 s[28:29], s[2:3], 1
	s_add_u32 s2, s5, s28
	v_writelane_b32 v250, s5, 48
	s_addc_u32 s3, s11, s29
	v_writelane_b32 v250, s11, 49
	s_add_u32 s2, s2, s4
	s_mul_hi_i32 s5, s1, 0x300000
	v_writelane_b32 v250, s2, 50
	s_addc_u32 s2, s3, s5
	v_writelane_b32 v250, s2, 51
	s_lshl_b32 s1, s1, 8
	v_writelane_b32 v250, s1, 52
	s_ashr_i32 s1, s0, 31
	s_lshl_b64 s[2:3], s[0:1], 12
	v_writelane_b32 v250, s2, 53
	s_lshl_b64 s[0:1], s[0:1], 22
	s_ashr_i32 s8, s8, 2
	v_writelane_b32 v250, s3, 54
	v_writelane_b32 v250, s0, 55
	s_nop 1
	v_writelane_b32 v250, s1, 56
	s_and_b32 s0, s21, 3
	s_lshl_b32 s2, s0, 10
	s_lshl_b32 s30, s0, 11
	v_writelane_b32 v250, s9, 57
	s_add_u32 s11, s9, s30
	v_writelane_b32 v250, s12, 58
	s_addc_u32 s12, s12, 0
	s_ashr_i32 s9, s8, 31
	s_lshl_b32 s3, s0, 20
	s_lshl_b64 s[0:1], s[8:9], 21
	s_add_u32 s9, s11, s0
	v_writelane_b32 v250, s9, 59
	s_addc_u32 s9, s12, s1
	v_writelane_b32 v250, s9, 60
	s_lshl_b32 s8, s8, 8
	v_writelane_b32 v250, s8, 61
	s_cmpk_lt_i32 s15, 0xc80
	v_writelane_b32 v250, s15, 62
	s_cselect_b64 s[8:9], -1, 0
	v_writelane_b32 v250, s8, 63
	s_nop 1
	v_writelane_b32 v251, s9, 0
	s_add_u32 s8, s48, 0x1e040000
	s_addc_u32 s9, s49, 0
	v_writelane_b32 v251, s8, 1
	v_readlane_b32 s36, v248, 10
	v_readlane_b32 s50, v248, 24
	v_writelane_b32 v251, s9, 2
	s_add_u32 s8, s22, 0xf300000
	s_addc_u32 s9, s23, 0
	s_lshl_b32 s34, s19, 4
	v_writelane_b32 v251, s8, 3
	s_cmp_lt_i32 s21, s34
	v_readlane_b32 s51, v248, 25
	v_writelane_b32 v251, s9, 4
	s_cselect_b64 s[8:9], -1, 0
	v_writelane_b32 v251, s8, 5
	s_add_i32 s16, s24, s6
	s_add_i32 s20, s19, -8
	v_writelane_b32 v251, s9, 6
	s_lshr_b32 s8, s14, 29
	s_add_i32 s8, s21, s8
	v_writelane_b32 v251, s14, 7
	s_ashr_i32 s14, s8, 3
	s_and_b32 s8, s8, -8
	s_sub_i32 s15, s21, s8
	s_add_i32 s17, s16, -1
	s_add_i32 s8, s13, s10
	s_cmpk_lt_i32 s8, 0x3c80
	v_writelane_b32 v251, s8, 8
	s_cselect_b64 s[8:9], -1, 0
	v_writelane_b32 v251, s8, 9
	v_readlane_b32 s48, v248, 22
	v_readlane_b32 s49, v248, 23
	v_writelane_b32 v251, s9, 10
	s_add_u32 s8, s22, 0x85300000
	s_addc_u32 s9, s23, 0
	s_lshl_b32 s31, s19, 1
	v_writelane_b32 v251, s8, 11
	s_add_i32 s18, s10, s33
	s_or_b32 s33, s31, 1
	v_writelane_b32 v251, s9, 12
	s_add_u32 s8, s22, 0x76d00000
	v_writelane_b32 v251, s8, 13
	s_addc_u32 s8, s23, 0
	v_writelane_b32 v251, s8, 14
	s_add_u32 s8, s50, 0x4000
	s_addc_u32 s9, s51, 0
	v_writelane_b32 v251, s8, 15
	v_mov_b32_e32 v1, s15
	v_alignbit_b32 v1, s19, v1, 31
	v_writelane_b32 v251, s9, 16
	s_add_u32 s8, s48, 0x4000
	s_addc_u32 s9, s49, 0
	v_writelane_b32 v251, s8, 17
	v_readlane_b32 s37, v248, 11
	v_readlane_b32 s38, v248, 12
	v_writelane_b32 v251, s9, 18
	v_readlane_b32 s8, v248, 3
	v_readlane_b32 s9, v248, 4
	s_mov_b64 s[12:13], s[8:9]
	s_cmp_gt_i32 s12, 7
	v_readlane_b32 s10, v248, 5
	v_readlane_b32 s11, v248, 6
	s_cselect_b64 s[8:9], -1, 0
	s_cmp_lt_i32 s13, 9
	s_cselect_b64 s[10:11], -1, 0
	s_cmpk_lt_i32 s21, 0xc0
	s_cselect_b32 s7, s7, -1
	s_cmpk_gt_i32 s24, 0xc0
	s_cselect_b32 s7, s7, -2
	s_cmp_lg_u32 s7, 1
	s_cselect_b64 s[12:13], -1, 0
	v_writelane_b32 v251, s26, 19
	s_and_b64 s[12:13], s[26:27], s[12:13]
	s_cmp_lg_u32 s7, 2
	v_writelane_b32 v251, s27, 20
	v_writelane_b32 v251, s12, 21
	v_readlane_b32 s39, v248, 13
	v_readlane_b32 s40, v248, 14
	v_writelane_b32 v251, s13, 22
	v_writelane_b32 v251, s7, 23
	v_readfirstlane_b32 s7, v1
	v_writelane_b32 v251, s19, 24
	s_mul_i32 s7, s7, s15
	s_cselect_b64 s[12:13], -1, 0
	v_writelane_b32 v251, s12, 25
	s_add_i32 s7, s7, s14
	v_readlane_b32 s41, v248, 15
	v_writelane_b32 v251, s13, 26
	s_ashr_i32 s12, s7, 31
	s_lshr_b32 s12, s12, 25
	s_add_i32 s12, s7, s12
	s_ashr_i32 s12, s12, 7
	s_lshl_b32 s13, s12, 7
	s_sub_i32 s7, s7, s13
	s_lshl_b32 s12, s12, 3
	s_cmp_gt_i32 s12, s20
	s_cselect_b32 s13, 1, 8
	s_cmp_lt_i32 s15, 0
	s_cselect_b32 s19, s33, s31
	s_mul_i32 s15, s19, s15
	s_add_i32 s14, s15, s14
	v_cvt_f32_ubyte0_e32 v1, s13
	s_ashr_i32 s15, s14, 31
	v_rcp_iflag_f32_e32 v1, v1
	s_lshr_b32 s15, s15, 25
	s_add_i32 s15, s14, s15
	s_ashr_i32 s15, s15, 7
	s_lshl_b32 s19, s15, 7
	v_mul_f32_e32 v1, 0x4f7ffffe, v1
	v_writelane_b32 v251, s31, 27
	s_sub_i32 s14, s14, s19
	s_lshl_b32 s15, s15, 3
	v_cvt_u32_f32_e32 v1, v1
	v_writelane_b32 v251, s33, 28
	s_cmp_gt_i32 s15, s20
	v_writelane_b32 v251, s20, 29
	s_cselect_b32 s19, 1, 8
	s_or_b64 s[8:9], s[8:9], s[10:11]
	v_writelane_b32 v251, s8, 30
	s_mov_b32 s33, 0xbcf5c28f
	v_readlane_b32 s42, v248, 16
	v_writelane_b32 v251, s9, 31
	s_sub_i32 s8, 0, s13
	v_readfirstlane_b32 s9, v1
	s_mul_i32 s8, s8, s9
	s_mul_hi_u32 s8, s9, s8
	s_add_i32 s9, s9, s8
	s_abs_i32 s8, s7
	s_mul_hi_u32 s9, s8, s9
	s_mul_i32 s10, s9, s13
	s_sub_i32 s8, s8, s10
	s_ashr_i32 s10, s7, 31
	s_add_i32 s11, s9, 1
	s_sub_i32 s20, s8, s13
	s_cmp_ge_u32 s8, s13
	s_cselect_b32 s9, s11, s9
	s_cselect_b32 s8, s20, s8
	s_add_i32 s11, s9, 1
	s_cmp_ge_u32 s8, s13
	s_cselect_b32 s8, s11, s9
	s_xor_b32 s8, s8, s10
	s_sub_i32 s8, s8, s10
	v_writelane_b32 v251, s8, 32
	s_mul_i32 s8, s8, s13
	s_sub_i32 s7, s7, s8
	s_add_i32 s7, s12, s7
	v_writelane_b32 v251, s7, 33
	s_abs_i32 s7, s24
	v_cvt_f32_u32_e32 v1, s7
	s_sub_i32 s8, 0, s7
	v_readlane_b32 s43, v248, 17
	v_readlane_b32 s44, v248, 18
	v_rcp_iflag_f32_e32 v1, v1
	v_readlane_b32 s45, v248, 19
	v_readlane_b32 s46, v248, 20
	v_readlane_b32 s47, v248, 21
	v_mul_f32_e32 v1, 0x4f7ffffe, v1
	v_cvt_u32_f32_e32 v1, v1
	s_nop 0
	v_readfirstlane_b32 s9, v1
	s_mul_i32 s8, s8, s9
	s_mul_hi_u32 s8, s9, s8
	s_add_i32 s9, s9, s8
	s_sub_i32 s8, 1, s16
	s_max_i32 s8, s17, s8
	s_mul_hi_u32 s9, s8, s9
	s_mul_i32 s10, s9, s7
	s_sub_i32 s8, s8, s10
	s_xor_b32 s10, s17, s24
	s_ashr_i32 s10, s10, 31
	s_add_i32 s11, s9, 1
	s_sub_i32 s12, s8, s7
	s_cmp_ge_u32 s8, s7
	s_cselect_b32 s9, s11, s9
	s_cselect_b32 s8, s12, s8
	s_add_i32 s11, s9, 1
	s_cmp_ge_u32 s8, s7
	s_cselect_b32 s7, s11, s9
	s_xor_b32 s7, s7, s10
	s_not_b32 s8, s10
	s_add_i32 s7, s8, s7
	s_mul_i32 s7, s7, s24
	s_sub_i32 s6, s6, s7
	s_sub_i32 s7, s24, s6
	v_cvt_f32_ubyte0_e32 v1, s19
	s_cmp_lt_i32 s7, 1
	v_rcp_iflag_f32_e32 v1, v1
	s_cselect_b64 s[8:9], -1, 0
	v_writelane_b32 v251, s8, 34
	s_cmp_ge_i32 s21, s6
	v_mul_f32_e32 v1, 0x4f7ffffe, v1
	v_writelane_b32 v251, s9, 35
	s_cselect_b64 s[8:9], -1, 0
	s_sub_i32 s6, s21, s6
	v_writelane_b32 v251, s8, 36
	s_lshl_b32 s6, s6, 3
	s_add_i32 s6, s18, s6
	v_writelane_b32 v251, s9, 37
	s_lshl_b32 s7, s7, 3
	v_cvt_u32_f32_e32 v1, v1
	v_writelane_b32 v251, s7, 38
	s_cmpk_lt_i32 s6, 0x3c80
	v_writelane_b32 v251, s6, 39
	s_cselect_b64 s[6:7], -1, 0
	v_writelane_b32 v251, s6, 40
	s_nop 1
	v_writelane_b32 v251, s7, 41
	s_sub_i32 s6, 0, s19
	v_readfirstlane_b32 s7, v1
	s_mul_i32 s6, s6, s7
	s_mul_hi_u32 s6, s7, s6
	s_add_i32 s7, s7, s6
	s_abs_i32 s6, s14
	s_mul_hi_u32 s7, s6, s7
	s_mul_i32 s8, s7, s19
	s_sub_i32 s6, s6, s8
	s_ashr_i32 s8, s14, 31
	s_add_i32 s9, s7, 1
	s_sub_i32 s10, s6, s19
	s_cmp_ge_u32 s6, s19
	s_cselect_b32 s7, s9, s7
	s_cselect_b32 s6, s10, s6
	s_add_i32 s9, s7, 1
	s_cmp_ge_u32 s6, s19
	s_cselect_b32 s6, s9, s7
	s_xor_b32 s6, s6, s8
	s_sub_i32 s8, s6, s8
	s_mul_i32 s6, s8, s19
	s_sub_i32 s6, s14, s6
	s_add_i32 s10, s15, s6
	s_lshl_b32 s6, s21, 8
	v_writelane_b32 v251, s6, 42
	s_lshl_b32 s6, s24, 8
	v_writelane_b32 v251, s6, 43
	v_writelane_b32 v251, s25, 44
	s_lshl_b32 s6, s25, 8
	v_writelane_b32 v251, s6, 45
	s_mov_b32 s6, s10
	s_ashr_i32 s11, s10, 31
	v_writelane_b32 v251, s6, 46
	s_ashr_i32 s9, s8, 31
	v_mbcnt_lo_u32_b32 v1, -1, 0
	v_writelane_b32 v251, s7, 47
	s_lshl_b64 s[6:7], s[10:11], 21
	v_writelane_b32 v251, s6, 48
	v_mbcnt_hi_u32_b32 v229, -1, v1
	s_nop 0
	v_writelane_b32 v251, s7, 49
	s_mov_b32 s6, s8
	v_writelane_b32 v251, s6, 50
	s_nop 1
	v_writelane_b32 v251, s7, 51
	s_lshl_b64 s[6:7], s[8:9], 21
	s_add_u32 s4, s4, s28
	s_addc_u32 s5, s5, s29
	s_add_u32 s4, s22, s4
	v_writelane_b32 v251, s6, 52
	s_addc_u32 s5, s23, s5
	s_add_u32 s4, s4, 0x1e500100
	v_writelane_b32 v251, s7, 53
	v_writelane_b32 v251, s4, 54
	s_addc_u32 s4, s5, 0
	v_writelane_b32 v251, s4, 55
	s_add_u32 s4, s28, 0x55b80080
	v_writelane_b32 v251, s4, 56
	v_writelane_b32 v251, s28, 57
	s_addc_u32 s4, s29, 0
	s_or_b32 s0, s0, s30
	v_writelane_b32 v251, s29, 58
	s_mov_b32 s5, 0
	v_writelane_b32 v251, s4, 59
	s_add_u32 s0, s22, s0
	s_mov_b32 s35, s5
	s_addc_u32 s1, s23, s1
	v_writelane_b32 v251, s34, 60
	s_add_u32 s0, s0, 0x24500100
	s_mov_b64 s[6:7], -1
	v_writelane_b32 v251, s35, 61
	v_writelane_b32 v251, s0, 62
	s_addc_u32 s0, s1, 0
	v_writelane_b32 v251, s0, 63
	s_mul_hi_i32 s1, s66, 0x3000
	s_mul_i32 s0, s66, 0x3000
	v_writelane_b32 v252, s0, 0
	s_ashr_i32 s67, s66, 31
	s_mov_b32 s12, s5
	v_writelane_b32 v252, s1, 1
	s_lshl_b32 s0, s2, 1
	v_writelane_b32 v252, s0, 2
	s_lshl_b32 s0, s3, 2
	v_writelane_b32 v252, s0, 3
	v_writelane_b32 v252, s30, 4
	s_or_b32 s0, s30, 0x6a800080
	v_writelane_b32 v252, s0, 5
	s_add_i32 s0, 0, 0x19800
	v_writelane_b32 v252, s0, 6
	v_cmp_eq_u32_e64 s[0:1], 0, v0
	s_mov_b64 s[2:3], 0x80
	s_nop 0
	v_writelane_b32 v252, s0, 7
	s_nop 1
	v_writelane_b32 v252, s1, 8
	s_lshl_b64 s[0:1], s[66:67], 12
	v_writelane_b32 v252, s0, 9
	s_nop 1
	v_writelane_b32 v252, s1, 10
	s_lshl_b64 s[0:1], s[66:67], 7
	v_writelane_b32 v252, s0, 11
	s_nop 1
	v_writelane_b32 v252, s1, 12
	s_lshl_b64 s[0:1], s[66:67], 13
	v_writelane_b32 v252, s0, 13
	s_nop 1
	v_writelane_b32 v252, s1, 14
	s_mov_b32 s1, 0
	v_writelane_b32 v252, s0, 15
	s_nop 1
	v_writelane_b32 v252, s1, 16
	v_writelane_b32 v252, s66, 17
	s_nop 1
	v_writelane_b32 v252, s67, 18
	s_branch .LBB0_84
